# MLA attention DMA also via SGPR bases (K and V base, branch-free select for the wave-dependent piece)
# baseline (speedup 1.0000x reference)
; DI unsigned cvtpk(float lo, float hi) { f32x2 v = {lo, hi}; bf16x2_t b = __builtin_convertvector(v, bf16x2_t); return __builtin_bit_cast(unsigned, b); }
; template <int DQK, int DV, int kpitch, int vpitch>
; DI void attn_map(LAS unsigned char* lds, const bf16x8 (&qf)[DQK / 16], const bf16* Kg, const bf16* Vg, f32x16 (&o)[DV / 32], float& lsum, int tid, int lane) {
;     ...
;     const bf16* src[4]; int step[4];
; #pragma unroll
;     for (int j = 0; j < 4; ++j) { int ci = (j * 8 + wave) * 64 + lane;
;         if (ci < NKCH) { const int row = ci / KCH, cc = ci % KCH; src[j] = Kg + (size_t)row * kpitch + (cc < KC ? cc : 0) * 8; step[j] = 64 * kpitch; }
;         else if (ci < NKCH + NVCH) { ci -= NKCH; const int row = ci / VCH, cc = ci % VCH; src[j] = Vg + (size_t)row * vpitch + (cc < VC ? cc : 0) * 8; step[j] = 64 * vpitch; }
;         else { src[j] = Kg; step[j] = 64 * kpitch; } }
;     ...
;     const int r = lane & 31, h = lane >> 5;
;     const int koff = r * KSTR + h * 16;
;     const int voff = KBUF + (4 * h + ((lane & 15) >> 2)) * VSTR + (((lane >> 4) & 1) * 16 + (lane & 3) * 4) * 2;
;     float l0 = 0.f, l1 = 0.f, l2 = 0.f, l3 = 0.f;
; #pragma unroll
;     for (int d = 0; d < DV / 32; ++d)
; #pragma unroll
;         for (int i = 0; i < 16; ++i) o[d][i] = 0.f;
; DI void mla_unit(const Params& p, LAS unsigned char* lds, int b, int head, int qb, int tid, int lane, int wave) {
;     ...
;     const int r = lane & 31, h = lane >> 5; const size_t row = (size_t)b * SEQ + qb * 256 + wave * 32 + r;
;     const float sq = rsqrtf((QSSN[row * 8 + head] + QSSP[row * 8 + head]) * (1.f / 96.f) + EPS) * (LOG2E * 0.10206207261596575f);
;     bf16x8 qf[6];
; #pragma unroll
;     for (int ks = 0; ks < 6; ++ks) { const bf16x8 raw = *(const bf16x8*)(QM + row * 768 + head * 96 + ks * 16 + h * 8); u32x4 w;
;         w.x = cvtpk(bf2f(raw[0]) * sq, bf2f(raw[1]) * sq); w.y = cvtpk(bf2f(raw[2]) * sq, bf2f(raw[3]) * sq); w.z = cvtpk(bf2f(raw[4]) * sq, bf2f(raw[5]) * sq); w.w = cvtpk(bf2f(raw[6]) * sq, bf2f(raw[7]) * sq);
;         qf[ks] = __builtin_bit_cast(bf16x8, w); }
;     f32x16 o[2]; float l;
;     attn_map<96, 64, 768, 512>(lds, qf, KM + (size_t)b * SEQ * 768 + head * 96, VM + (size_t)b * SEQ * 512 + head * 64, o, l, tid, lane);
.LBB0_1951:
	s_waitcnt vmcnt(0)
	v_add_f32_e32 v26, v26, v27
	v_fmamk_f32 v26, v26, 0x3c2aaaab, v232
	v_mul_f32_e32 v27, 0x4b800000, v26
	v_cmp_gt_f32_e32 vcc, s74, v26
	v_bfe_u32 v28, v150, 2, 2
	v_lshlrev_b32_e32 v30, 4, v25
	v_cndmask_b32_e32 v26, v26, v27, vcc
	v_rsq_f32_e32 v26, v26
	v_lshl_or_b32 v25, v25, 2, v28
	v_and_b32_e32 v27, 16, v150
	v_lshlrev_b32_e32 v28, 2, v150
	v_and_or_b32 v27, v28, 12, v27
	v_mul_f32_e32 v28, 0x45800000, v26
	v_cndmask_b32_e32 v26, v26, v28, vcc
	v_mul_f32_e32 v26, 0x3e16c740, v26
	v_and_b32_e32 v29, 0xffff0000, v20
	v_lshlrev_b32_e32 v28, 16, v20
	v_pk_mul_f32 v[28:29], v[26:27], v[28:29] op_sel_hi:[0,1]
	v_cvt_pk_bf16_f32 v104, v28, v29
	v_and_b32_e32 v29, 0xffff0000, v21
	v_lshlrev_b32_e32 v28, 16, v21
	v_pk_mul_f32 v[20:21], v[26:27], v[28:29] op_sel_hi:[0,1]
	v_cvt_pk_bf16_f32 v105, v20, v21
	v_and_b32_e32 v21, 0xffff0000, v22
	v_lshlrev_b32_e32 v20, 16, v22
	v_pk_mul_f32 v[20:21], v[26:27], v[20:21] op_sel_hi:[0,1]
	v_cvt_pk_bf16_f32 v106, v20, v21
	v_and_b32_e32 v21, 0xffff0000, v23
	v_lshlrev_b32_e32 v20, 16, v23
	v_pk_mul_f32 v[20:21], v[26:27], v[20:21] op_sel_hi:[0,1]
	v_cvt_pk_bf16_f32 v107, v20, v21
	v_and_b32_e32 v21, 0xffff0000, v16
	v_lshlrev_b32_e32 v20, 16, v16
	v_pk_mul_f32 v[20:21], v[26:27], v[20:21] op_sel_hi:[0,1]
	v_cvt_pk_bf16_f32 v108, v20, v21
	v_and_b32_e32 v21, 0xffff0000, v17
	v_lshlrev_b32_e32 v20, 16, v17
	v_pk_mul_f32 v[16:17], v[26:27], v[20:21] op_sel_hi:[0,1]
	v_cvt_pk_bf16_f32 v109, v16, v17
	v_and_b32_e32 v17, 0xffff0000, v18
	v_lshlrev_b32_e32 v16, 16, v18
	v_pk_mul_f32 v[16:17], v[26:27], v[16:17] op_sel_hi:[0,1]
	v_cvt_pk_bf16_f32 v110, v16, v17
	v_and_b32_e32 v17, 0xffff0000, v19
	v_lshlrev_b32_e32 v16, 16, v19
	v_pk_mul_f32 v[16:17], v[26:27], v[16:17] op_sel_hi:[0,1]
	v_cvt_pk_bf16_f32 v111, v16, v17
	v_and_b32_e32 v17, 0xffff0000, v12
	v_lshlrev_b32_e32 v16, 16, v12
	v_pk_mul_f32 v[16:17], v[26:27], v[16:17] op_sel_hi:[0,1]
	v_cvt_pk_bf16_f32 v112, v16, v17
	v_and_b32_e32 v17, 0xffff0000, v13
	v_lshlrev_b32_e32 v16, 16, v13
	v_pk_mul_f32 v[12:13], v[26:27], v[16:17] op_sel_hi:[0,1]
	v_cvt_pk_bf16_f32 v113, v12, v13
	v_and_b32_e32 v13, 0xffff0000, v14
	v_lshlrev_b32_e32 v12, 16, v14
	v_pk_mul_f32 v[12:13], v[26:27], v[12:13] op_sel_hi:[0,1]
	v_cvt_pk_bf16_f32 v114, v12, v13
	v_and_b32_e32 v13, 0xffff0000, v15
	v_lshlrev_b32_e32 v12, 16, v15
	v_pk_mul_f32 v[12:13], v[26:27], v[12:13] op_sel_hi:[0,1]
	v_cvt_pk_bf16_f32 v115, v12, v13
	v_and_b32_e32 v13, 0xffff0000, v8
	v_lshlrev_b32_e32 v12, 16, v8
	v_pk_mul_f32 v[12:13], v[26:27], v[12:13] op_sel_hi:[0,1]
	v_cvt_pk_bf16_f32 v116, v12, v13
	v_and_b32_e32 v13, 0xffff0000, v9
	v_lshlrev_b32_e32 v12, 16, v9
	v_pk_mul_f32 v[8:9], v[26:27], v[12:13] op_sel_hi:[0,1]
	v_cvt_pk_bf16_f32 v117, v8, v9
	v_and_b32_e32 v9, 0xffff0000, v10
	v_lshlrev_b32_e32 v8, 16, v10
	v_pk_mul_f32 v[8:9], v[26:27], v[8:9] op_sel_hi:[0,1]
	v_cvt_pk_bf16_f32 v118, v8, v9
	v_and_b32_e32 v9, 0xffff0000, v11
	v_lshlrev_b32_e32 v8, 16, v11
	v_pk_mul_f32 v[8:9], v[26:27], v[8:9] op_sel_hi:[0,1]
	v_cvt_pk_bf16_f32 v119, v8, v9
	v_and_b32_e32 v9, 0xffff0000, v4
	v_lshlrev_b32_e32 v8, 16, v4
	v_pk_mul_f32 v[8:9], v[26:27], v[8:9] op_sel_hi:[0,1]
	v_cvt_pk_bf16_f32 v120, v8, v9
	v_and_b32_e32 v9, 0xffff0000, v5
	v_lshlrev_b32_e32 v8, 16, v5
	v_pk_mul_f32 v[4:5], v[26:27], v[8:9] op_sel_hi:[0,1]
	v_cvt_pk_bf16_f32 v121, v4, v5
	v_and_b32_e32 v5, 0xffff0000, v6
	v_lshlrev_b32_e32 v4, 16, v6
	v_pk_mul_f32 v[4:5], v[26:27], v[4:5] op_sel_hi:[0,1]
	v_cvt_pk_bf16_f32 v122, v4, v5
	v_and_b32_e32 v5, 0xffff0000, v7
	v_lshlrev_b32_e32 v4, 16, v7
	v_pk_mul_f32 v[4:5], v[26:27], v[4:5] op_sel_hi:[0,1]
	v_cvt_pk_bf16_f32 v123, v4, v5
	v_and_b32_e32 v5, 0xffff0000, v0
	v_lshlrev_b32_e32 v4, 16, v0
	v_pk_mul_f32 v[4:5], v[26:27], v[4:5] op_sel_hi:[0,1]
	v_cvt_pk_bf16_f32 v124, v4, v5
	v_and_b32_e32 v5, 0xffff0000, v1
	v_lshlrev_b32_e32 v4, 16, v1
	v_pk_mul_f32 v[0:1], v[26:27], v[4:5] op_sel_hi:[0,1]
	v_cvt_pk_bf16_f32 v125, v0, v1
	v_and_b32_e32 v1, 0xffff0000, v2
	v_lshlrev_b32_e32 v0, 16, v2
	v_pk_mul_f32 v[0:1], v[26:27], v[0:1] op_sel_hi:[0,1]
	s_movk_i32 s10, 0xc0
	v_cvt_pk_bf16_f32 v126, v0, v1
	v_and_b32_e32 v1, 0xffff0000, v3
	v_lshlrev_b32_e32 v0, 16, v3
	v_mul_lo_u32 v25, v25, s10
	v_pk_mul_f32 v[0:1], v[26:27], v[0:1] op_sel_hi:[0,1]
	s_movk_i32 s10, 0xd0
	v_mov_b32_e32 v147, 0
	s_lshl_b32 s13, s13, 6
	v_cvt_pk_bf16_f32 v127, v0, v1
	v_mad_u32_u24 v151, v24, s10, v30
	s_lshl_b32 s23, s23, 10
	s_lshl_b32 s24, s24, 10
	s_lshl_b32 s25, s25, 10
	v_lshl_or_b32 v152, v27, 1, v25
	s_mov_b32 s27, 0
	v_mov_b32_e32 v149, 0
	v_mov_b32_e32 v146, 0
	v_mov_b32_e32 v148, 0
	v_mov_b32_e32 v16, 0
	v_mov_b32_e32 v17, v147
	v_mov_b32_e32 v18, v147
	v_mov_b32_e32 v19, v147
	v_mov_b32_e32 v20, v147
	v_mov_b32_e32 v21, v147
	v_mov_b32_e32 v22, v147
	v_mov_b32_e32 v23, v147
	v_mov_b32_e32 v24, v147
	v_mov_b32_e32 v25, v147
	v_mov_b32_e32 v26, v147
	v_mov_b32_e32 v27, v147
	v_mov_b32_e32 v28, v147
	v_mov_b32_e32 v29, v147
	v_mov_b32_e32 v30, v147
	v_mov_b32_e32 v31, v147
	v_mov_b32_e32 v0, 0
	v_mov_b32_e32 v1, v147
	v_mov_b32_e32 v2, v147
	v_mov_b32_e32 v3, v147
	v_mov_b32_e32 v4, v147
	v_mov_b32_e32 v5, v147
	v_mov_b32_e32 v6, v147
	v_mov_b32_e32 v7, v147
	v_mov_b32_e32 v8, v147
	v_mov_b32_e32 v9, v147
	v_mov_b32_e32 v10, v147
	v_mov_b32_e32 v11, v147
	v_mov_b32_e32 v12, v147
	v_mov_b32_e32 v13, v147
	v_mov_b32_e32 v14, v147
	v_mov_b32_e32 v15, v147
	v_readfirstlane_b32 s86, v32
	v_readfirstlane_b32 s87, v33
	v_readfirstlane_b32 s98, v34
	v_readfirstlane_b32 s99, v35
	v_readfirstlane_b32 s10, v36
	v_readfirstlane_b32 s11, v37
	s_nop 0
	s_sub_u32 s86, s86, 0x100
	s_subb_u32 s87, s87, 0
	s_cmp_le_u32 s23, 0x1000
	s_cselect_b32 s88, 1, 0
	s_cselect_b32 s98, s10, s98
	s_cselect_b32 s99, s11, s99
	s_sub_u32 s98, s98, 0x100
	s_subb_u32 s99, s99, 0
	s_cmp_eq_u32 s88, 1
	s_cselect_b32 s10, s86, s98
	v_subrev_u32_e32 v96, s86, v32
	v_subrev_u32_e32 v98, s10, v34
	v_subrev_u32_e32 v100, s98, v36
	v_subrev_u32_e32 v102, s98, v38
	s_branch .LBB0_1953
; #define LAS __attribute__((address_space(3)))
; #define MFMA32(a, b, c) __builtin_amdgcn_mfma_f32_32x32x16_bf16((a), (b), (c), 0, 0, 0)
; #define VTR_SET(lo, hi, c) do { _Pragma("unroll") for (int d = 0; d < ND; ++d) { \
;         VTR_ASM(lo[d], va, (32 * ((c) >> 1) + 16 * ((c) & 1)) * VSTR + d * 64); VTR_ASM(hi[d], va, (32 * ((c) >> 1) + 16 * ((c) & 1)) * VSTR + d * 64 + 8 * VSTR); } } while (0)
; #define PV_MMA(lo, hi, c) do { _Pragma("unroll") for (int d = 0; d < ND; ++d) { const bf16x8 vf = __builtin_shufflevector(lo[d], hi[d], 0, 1, 2, 3, 4, 5, 6, 7); o[d] = MFMA32(vf, pf[(c) >> 1][(c) & 1], o[d]); } } while (0)
; #define VTR_SET(lo, hi, base, c) do { _Pragma("unroll") for (int d = 0; d < ND; ++d) { \
;         VTR_ASM(lo[d], base, (32 * ((c) >> 1) + 16 * ((c) & 1)) * VSTR + d * 64); VTR_ASM(hi[d], base, (32 * ((c) >> 1) + 16 * ((c) & 1)) * VSTR + d * 64 + 8 * VSTR); } } while (0)
; template <int DQK, int DV, int KSTR, int VSTR>
; DI void attn_step2(const LAS unsigned char* ta, const LAS unsigned char* tb, int koff, int voff, const bf16x8 (&qf)[DQK / 16], f32x16 (&o)[DV / 32], float& l0, float& l1, float& l2, float& l3) {
;     ...
;     f32x16 sa[2], sb[2]; f32x16 zero16;
; #pragma unroll
;     for (int i = 0; i < 16; ++i) zero16[i] = 0.f;
; #pragma unroll
;     for (int ks = 0; ks < NKS; ++ks) {
;         const bf16x8 k0 = *(const LAS bf16x8*)(ta + koff + ks * 32), k1 = *(const LAS bf16x8*)(ta + koff + 32 * KSTR + ks * 32);
;         sa[0] = MFMA32(k0, qf[ks], ks == 0 ? zero16 : sa[0]); sa[1] = MFMA32(k1, qf[ks], ks == 0 ? zero16 : sa[1]);
;     }
;     const unsigned va = (unsigned)(uintptr_t)(ta + voff), vb = (unsigned)(uintptr_t)(tb + voff);
;     s16x4 alo[ND], ahi[ND], blo[ND], bhi[ND];
;     ...
;     VTR_SET(alo, ahi, va, 0);
;     bf16x8 pfa[4], pfb[4];
; #pragma unroll
;     for (int c = 0; c < 4; ++c) {
; #pragma unroll
;         for (int ks = (c * NKS) / 4; ks < ((c + 1) * NKS) / 4; ++ks) {
;             const bf16x8 k0 = *(const LAS bf16x8*)(tb + koff + ks * 32), k1 = *(const LAS bf16x8*)(tb + koff + 32 * KSTR + ks * 32);
;             sb[0] = MFMA32(k0, qf[ks], ks == 0 ? zero16 : sb[0]); sb[1] = MFMA32(k1, qf[ks], ks == 0 ? zero16 : sb[1]);
;         }
;         SM_CHUNK(sa, pfa[c], c);
;     }
;     vtr_wait<ND>(alo, ahi); VTR_SET(blo, bhi, va, 1); PV_MMA(alo, ahi, pfa[0]); SM_CHUNK(sb, pfb[0], 0);
.LBB0_1952:
	s_and_b32 s10, s27, 0x10000
	v_add_u32_e32 v154, s10, v151
	v_add_u32_e32 v153, s10, v152
	v_add_u32_e32 v153, 0x3400, v153
	s_and_b32 s11, s26, 0x10000
	s_cmp_eq_u32 s27, 0xf0000
	s_cselect_b64 s[16:17], -1, 0
	ds_read_b128 v[206:209], v154
	ds_read_b128 v[210:213], v154 offset:32
	ds_read_b128 v[214:217], v154 offset:64
	ds_read_b128 v[218:221], v154 offset:96
	ds_read_b128 v[222:225], v154 offset:128
	ds_read_b128 v[226:229], v154 offset:160
	s_waitcnt lgkmcnt(5)
	v_mfma_f32_32x32x16_bf16 v[32:47], v[206:209], v[104:107], 0
	ds_read_b128 v[206:209], v154 offset:6656
	s_or_b64 s[44:45], s[16:17], s[0:1]
	s_cbranch_scc1 .Lmla_dma_skip_0
	s_add_i32 m0, s11, s23
	s_nop 0
	global_load_lds_dwordx4 v96, s[86:87]
.Lmla_dma_skip_0:
	s_waitcnt lgkmcnt(5)
	v_mfma_f32_32x32x16_bf16 v[32:47], v[210:213], v[108:111], v[32:47]
	ds_read_b128 v[210:213], v154 offset:6688
	s_or_b64 s[44:45], s[16:17], s[38:39]
	s_cbranch_scc1 .Lmla_dma_skip_1
	s_add_i32 m0, s11, s24
	s_nop 0
	s_cmp_eq_u32 s88, 1
	s_cselect_b64 s[44:45], s[86:87], s[98:99]
	global_load_lds_dwordx4 v98, s[44:45]
.Lmla_dma_skip_1:
	s_waitcnt lgkmcnt(5)
	v_mfma_f32_32x32x16_bf16 v[32:47], v[214:217], v[112:115], v[32:47]
	ds_read_b128 v[214:217], v154 offset:6720
	s_or_b64 s[44:45], s[16:17], s[42:43]
	s_cbranch_scc1 .Lmla_dma_skip_2
	s_add_i32 m0, s11, s25
	s_nop 0
	global_load_lds_dwordx4 v100, s[98:99]
.Lmla_dma_skip_2:
	s_waitcnt lgkmcnt(5)
	v_mfma_f32_32x32x16_bf16 v[32:47], v[218:221], v[116:119], v[32:47]
	ds_read_b128 v[218:221], v154 offset:6752
	s_orn2_b64 s[44:45], s[16:17], s[14:15]
	s_cbranch_scc1 .Lmla_dma_skip_3
	s_add_i32 m0, s11, s22
	s_nop 0
	global_load_lds_dwordx4 v102, s[98:99]
.Lmla_dma_skip_3:
	s_add_u32 s86, s86, 0x18000
	s_addc_u32 s87, s87, 0
	s_add_u32 s98, s98, 0x10000
	s_addc_u32 s99, s99, 0
	s_waitcnt lgkmcnt(5)
	v_mfma_f32_32x32x16_bf16 v[32:47], v[222:225], v[120:123], v[32:47]
	ds_read_b128 v[222:225], v154 offset:6784
	s_or_b64 s[44:45], s[16:17], s[0:1]
	s_cbranch_scc1 .Lmla_dma_skip_4
	s_add_i32 s10, s11, s23
	s_add_i32 m0, s10, 0x8000
	s_nop 0
	global_load_lds_dwordx4 v96, s[86:87]
.Lmla_dma_skip_4:
	s_waitcnt lgkmcnt(5)
	v_mfma_f32_32x32x16_bf16 v[32:47], v[226:229], v[124:127], v[32:47]
	ds_read_b128 v[226:229], v154 offset:6816
	s_or_b64 s[44:45], s[16:17], s[38:39]
	s_cbranch_scc1 .Lmla_dma_skip_5
	s_add_i32 s10, s11, s24
	s_add_i32 m0, s10, 0x8000
	s_nop 0
	s_cmp_eq_u32 s88, 1
	s_cselect_b64 s[44:45], s[86:87], s[98:99]
	global_load_lds_dwordx4 v98, s[44:45]
.Lmla_dma_skip_5:
	s_waitcnt lgkmcnt(5)
	v_mfma_f32_32x32x16_bf16 v[48:63], v[206:209], v[104:107], 0
	ds_read_b128 v[206:209], v154 offset:32768
	s_or_b64 s[44:45], s[16:17], s[42:43]
	s_cbranch_scc1 .Lmla_dma_skip_6
	s_add_i32 s10, s11, s25
	s_add_i32 m0, s10, 0x8000
	s_nop 0
	global_load_lds_dwordx4 v100, s[98:99]
.Lmla_dma_skip_6:
	s_waitcnt lgkmcnt(5)
	v_mfma_f32_32x32x16_bf16 v[48:63], v[210:213], v[108:111], v[48:63]
	ds_read_b128 v[210:213], v154 offset:32800
	s_orn2_b64 s[44:45], s[16:17], s[14:15]
	s_cbranch_scc1 .Lmla_dma_skip_7
	s_add_i32 s10, s11, s22
	s_add_i32 m0, s10, 0x8000
	s_nop 0
	global_load_lds_dwordx4 v102, s[98:99]
.Lmla_dma_skip_7:
	s_add_u32 s86, s86, 0x18000
	s_addc_u32 s87, s87, 0
	s_add_u32 s98, s98, 0x10000
	s_addc_u32 s99, s99, 0
	v_exp_f32_e32 v32, v32
	v_exp_f32_e32 v33, v33
	v_exp_f32_e32 v34, v34
	v_exp_f32_e32 v35, v35
	s_waitcnt lgkmcnt(5)
	v_mfma_f32_32x32x16_bf16 v[48:63], v[214:217], v[112:115], v[48:63]
	ds_read_b128 v[214:217], v154 offset:32832
	v_exp_f32_e32 v36, v36
	v_exp_f32_e32 v37, v37
	v_exp_f32_e32 v38, v38
	v_exp_f32_e32 v39, v39
	s_waitcnt lgkmcnt(5)
	v_mfma_f32_32x32x16_bf16 v[48:63], v[218:221], v[116:119], v[48:63]
	ds_read_b128 v[218:221], v154 offset:32864
	v_exp_f32_e32 v40, v40
	v_exp_f32_e32 v41, v41
	v_exp_f32_e32 v42, v42
	v_exp_f32_e32 v43, v43
	s_waitcnt lgkmcnt(5)
	v_mfma_f32_32x32x16_bf16 v[48:63], v[222:225], v[120:123], v[48:63]
	ds_read_b128 v[222:225], v154 offset:32896
	v_exp_f32_e32 v44, v44
	v_exp_f32_e32 v45, v45
	v_exp_f32_e32 v46, v46
	v_exp_f32_e32 v47, v47
	s_waitcnt lgkmcnt(5)
	v_mfma_f32_32x32x16_bf16 v[48:63], v[226:229], v[124:127], v[48:63]
	ds_read_b128 v[226:229], v154 offset:32928
	v_cvt_pk_bf16_f32 v128, v32, v33
	v_cvt_pk_bf16_f32 v129, v34, v35
	v_cvt_pk_bf16_f32 v130, v36, v37
	v_cvt_pk_bf16_f32 v131, v38, v39
	v_cvt_pk_bf16_f32 v132, v40, v41
	v_cvt_pk_bf16_f32 v133, v42, v43
	v_cvt_pk_bf16_f32 v134, v44, v45
	s_waitcnt lgkmcnt(5)
	v_mfma_f32_32x32x16_bf16 v[64:79], v[206:209], v[104:107], 0
	ds_read_b128 v[206:209], v154 offset:39424
	v_cvt_pk_bf16_f32 v135, v46, v47
	v_exp_f32_e32 v48, v48
	v_exp_f32_e32 v49, v49
	v_exp_f32_e32 v50, v50
	s_waitcnt lgkmcnt(5)
	v_mfma_f32_32x32x16_bf16 v[64:79], v[210:213], v[108:111], v[64:79]
	ds_read_b128 v[210:213], v154 offset:39456
	ds_read_b64_tr_b16 v[194:195], v153
	ds_read_b64_tr_b16 v[196:197], v153 offset:1536
	v_exp_f32_e32 v51, v51
	v_exp_f32_e32 v52, v52
	v_exp_f32_e32 v53, v53
	v_exp_f32_e32 v54, v54
	s_waitcnt lgkmcnt(7)
	v_mfma_f32_32x32x16_bf16 v[64:79], v[214:217], v[112:115], v[64:79]
	ds_read_b128 v[214:217], v154 offset:39488
	ds_read_b64_tr_b16 v[198:199], v153 offset:64
	ds_read_b64_tr_b16 v[200:201], v153 offset:1600
	v_exp_f32_e32 v55, v55
	v_exp_f32_e32 v56, v56
	v_exp_f32_e32 v57, v57
	v_exp_f32_e32 v58, v58
	s_waitcnt lgkmcnt(9)
	v_mfma_f32_32x32x16_bf16 v[64:79], v[218:221], v[116:119], v[64:79]
	ds_read_b128 v[218:221], v154 offset:39520
	ds_read_b64_tr_b16 v[156:157], v153 offset:3072
	ds_read_b64_tr_b16 v[158:159], v153 offset:4608
	v_exp_f32_e32 v59, v59
	v_exp_f32_e32 v60, v60
	v_exp_f32_e32 v61, v61
	v_exp_f32_e32 v62, v62
	s_waitcnt lgkmcnt(11)
; #define VTR_SET(lo, hi, c) do { _Pragma("unroll") for (int d = 0; d < ND; ++d) { \
;         VTR_ASM(lo[d], va, (32 * ((c) >> 1) + 16 * ((c) & 1)) * VSTR + d * 64); VTR_ASM(hi[d], va, (32 * ((c) >> 1) + 16 * ((c) & 1)) * VSTR + d * 64 + 8 * VSTR); } } while (0)
; #define PV_MMA(lo, hi, c) do { _Pragma("unroll") for (int d = 0; d < ND; ++d) { const bf16x8 vf = __builtin_shufflevector(lo[d], hi[d], 0, 1, 2, 3, 4, 5, 6, 7); o[d] = MFMA32(vf, pf[(c) >> 1][(c) & 1], o[d]); } } while (0)
; #define VTR_SET(lo, hi, base, c) do { _Pragma("unroll") for (int d = 0; d < ND; ++d) { \
;         VTR_ASM(lo[d], base, (32 * ((c) >> 1) + 16 * ((c) & 1)) * VSTR + d * 64); VTR_ASM(hi[d], base, (32 * ((c) >> 1) + 16 * ((c) & 1)) * VSTR + d * 64 + 8 * VSTR); } } while (0)
; #define PV_MMA(lo, hi, pf_) do { _Pragma("unroll") for (int d = 0; d < ND; ++d) { const bf16x8 vf = __builtin_shufflevector(lo[d], hi[d], 0, 1, 2, 3, 4, 5, 6, 7); o[d] = MFMA32(vf, pf_, o[d]); } } while (0)
; template <int DQK, int DV, int KSTR, int VSTR>
; DI void attn_step2(const LAS unsigned char* ta, const LAS unsigned char* tb, int koff, int voff, const bf16x8 (&qf)[DQK / 16], f32x16 (&o)[DV / 32], float& l0, float& l1, float& l2, float& l3) {
;     ...
;         SM_CHUNK(sa, pfa[c], c);
;     }
;     vtr_wait<ND>(alo, ahi); VTR_SET(blo, bhi, va, 1); PV_MMA(alo, ahi, pfa[0]); SM_CHUNK(sb, pfb[0], 0);
;     vtr_wait<ND>(blo, bhi); VTR_SET(alo, ahi, va, 2); PV_MMA(blo, bhi, pfa[1]); SM_CHUNK(sb, pfb[1], 1);
;     vtr_wait<ND>(alo, ahi); VTR_SET(blo, bhi, va, 3); PV_MMA(alo, ahi, pfa[2]); SM_CHUNK(sb, pfb[2], 2);
;     vtr_wait<ND>(blo, bhi); VTR_SET(alo, ahi, vb, 0); PV_MMA(blo, bhi, pfa[3]); SM_CHUNK(sb, pfb[3], 3);
;     vtr_wait<ND>(alo, ahi); VTR_SET(blo, bhi, vb, 1); PV_MMA(alo, ahi, pfb[0]);
	v_mfma_f32_32x32x16_bf16 v[64:79], v[222:225], v[120:123], v[64:79]
	ds_read_b128 v[222:225], v154 offset:39552
	ds_read_b64_tr_b16 v[160:161], v153 offset:3136
	ds_read_b64_tr_b16 v[162:163], v153 offset:4672
	v_exp_f32_e32 v63, v63
	v_cvt_pk_bf16_f32 v168, v48, v49
	v_cvt_pk_bf16_f32 v169, v50, v51
	v_cvt_pk_bf16_f32 v170, v52, v53
	v_cvt_pk_bf16_f32 v171, v54, v55
	v_cvt_pk_bf16_f32 v172, v56, v57
	s_waitcnt lgkmcnt(13)
	v_mfma_f32_32x32x16_bf16 v[64:79], v[226:229], v[124:127], v[64:79]
	ds_read_b128 v[226:229], v154 offset:39584
	v_cvt_pk_bf16_f32 v173, v58, v59
	v_cvt_pk_bf16_f32 v174, v60, v61
	v_cvt_pk_bf16_f32 v175, v62, v63
	v_add_f32_e32 v146, v146, v32
	v_add_f32_e32 v147, v147, v33
	v_add_f32_e32 v148, v148, v34
	v_add_f32_e32 v149, v149, v35
	s_waitcnt lgkmcnt(10)
	v_mfma_f32_32x32x16_bf16 v[16:31], v[194:197], v[128:131], v[16:31]
	ds_read_b64_tr_b16 v[194:195], v153 offset:6144
	ds_read_b64_tr_b16 v[196:197], v153 offset:7680
	v_exp_f32_e32 v64, v64
	v_exp_f32_e32 v65, v65
	v_exp_f32_e32 v66, v66
	v_exp_f32_e32 v67, v67
	s_waitcnt lgkmcnt(9)
	v_mfma_f32_32x32x16_bf16 v[0:15], v[198:201], v[128:131], v[0:15]
	ds_read_b64_tr_b16 v[198:199], v153 offset:6208
	ds_read_b64_tr_b16 v[200:201], v153 offset:7744
	v_exp_f32_e32 v68, v68
	v_exp_f32_e32 v69, v69
	v_exp_f32_e32 v70, v70
	v_exp_f32_e32 v71, v71
	s_waitcnt lgkmcnt(8)
	v_mfma_f32_32x32x16_bf16 v[16:31], v[156:159], v[132:135], v[16:31]
	ds_read_b64_tr_b16 v[156:157], v153 offset:9216
	ds_read_b64_tr_b16 v[158:159], v153 offset:10752
	v_exp_f32_e32 v72, v72
	v_exp_f32_e32 v73, v73
	v_exp_f32_e32 v74, v74
	v_exp_f32_e32 v75, v75
	s_waitcnt lgkmcnt(7)
	v_mfma_f32_32x32x16_bf16 v[0:15], v[160:163], v[132:135], v[0:15]
	ds_read_b64_tr_b16 v[160:161], v153 offset:9280
	ds_read_b64_tr_b16 v[162:163], v153 offset:10816
	v_exp_f32_e32 v76, v76
	v_exp_f32_e32 v77, v77
	v_exp_f32_e32 v78, v78
	v_exp_f32_e32 v79, v79
	v_mfma_f32_32x32x16_bf16 v[80:95], v[206:209], v[104:107], 0
	v_cvt_pk_bf16_f32 v128, v64, v65
	v_cvt_pk_bf16_f32 v129, v66, v67
	v_cvt_pk_bf16_f32 v130, v68, v69
	v_cvt_pk_bf16_f32 v131, v70, v71
	v_cvt_pk_bf16_f32 v132, v72, v73
	v_cvt_pk_bf16_f32 v133, v74, v75
	v_cvt_pk_bf16_f32 v134, v76, v77
	v_mfma_f32_32x32x16_bf16 v[80:95], v[210:213], v[108:111], v[80:95]
	v_cvt_pk_bf16_f32 v135, v78, v79
	v_add_f32_e32 v146, v146, v36
	v_add_f32_e32 v147, v147, v37
	v_add_f32_e32 v148, v148, v38
	v_add_f32_e32 v149, v149, v39
	v_add_f32_e32 v146, v146, v40
	v_add_f32_e32 v147, v147, v41
	v_mfma_f32_32x32x16_bf16 v[80:95], v[214:217], v[112:115], v[80:95]
	v_add_f32_e32 v148, v148, v42
	v_add_f32_e32 v149, v149, v43
	v_add_f32_e32 v146, v146, v44
	v_add_f32_e32 v147, v147, v45
	v_add_f32_e32 v148, v148, v46
	v_add_f32_e32 v149, v149, v47
	v_add_f32_e32 v146, v146, v48
	v_mfma_f32_32x32x16_bf16 v[80:95], v[218:221], v[116:119], v[80:95]
	v_add_f32_e32 v147, v147, v49
	v_add_f32_e32 v148, v148, v50
	v_add_f32_e32 v149, v149, v51
	v_add_f32_e32 v146, v146, v52
	v_add_f32_e32 v147, v147, v53
	v_add_f32_e32 v148, v148, v54
	v_add_f32_e32 v149, v149, v55
	v_mfma_f32_32x32x16_bf16 v[80:95], v[222:225], v[120:123], v[80:95]
	v_add_f32_e32 v146, v146, v56
	v_add_f32_e32 v147, v147, v57
	v_add_f32_e32 v148, v148, v58
	v_add_f32_e32 v149, v149, v59
	v_add_f32_e32 v146, v146, v60
	v_add_f32_e32 v147, v147, v61
	v_add_f32_e32 v148, v148, v62
	s_waitcnt lgkmcnt(8)
	v_mfma_f32_32x32x16_bf16 v[80:95], v[226:229], v[124:127], v[80:95]
	v_add_f32_e32 v149, v149, v63
	v_add_f32_e32 v146, v146, v64
	v_add_f32_e32 v147, v147, v65
	v_add_f32_e32 v148, v148, v66
	v_add_f32_e32 v149, v149, v67
	v_add_f32_e32 v146, v146, v68
	v_add_f32_e32 v147, v147, v69
	s_waitcnt lgkmcnt(6)
; #define LAS __attribute__((address_space(3)))
; #define VTR_SET(lo, hi, c) do { _Pragma("unroll") for (int d = 0; d < ND; ++d) { \
;         VTR_ASM(lo[d], va, (32 * ((c) >> 1) + 16 * ((c) & 1)) * VSTR + d * 64); VTR_ASM(hi[d], va, (32 * ((c) >> 1) + 16 * ((c) & 1)) * VSTR + d * 64 + 8 * VSTR); } } while (0)
; #define PV_MMA(lo, hi, c) do { _Pragma("unroll") for (int d = 0; d < ND; ++d) { const bf16x8 vf = __builtin_shufflevector(lo[d], hi[d], 0, 1, 2, 3, 4, 5, 6, 7); o[d] = MFMA32(vf, pf[(c) >> 1][(c) & 1], o[d]); } } while (0)
; #define VTR_SET(lo, hi, base, c) do { _Pragma("unroll") for (int d = 0; d < ND; ++d) { \
;         VTR_ASM(lo[d], base, (32 * ((c) >> 1) + 16 * ((c) & 1)) * VSTR + d * 64); VTR_ASM(hi[d], base, (32 * ((c) >> 1) + 16 * ((c) & 1)) * VSTR + d * 64 + 8 * VSTR); } } while (0)
; #define PV_MMA(lo, hi, pf_) do { _Pragma("unroll") for (int d = 0; d < ND; ++d) { const bf16x8 vf = __builtin_shufflevector(lo[d], hi[d], 0, 1, 2, 3, 4, 5, 6, 7); o[d] = MFMA32(vf, pf_, o[d]); } } while (0)
; template <int DQK, int DV, int KSTR, int VSTR>
; DI void attn_step2(const LAS unsigned char* ta, const LAS unsigned char* tb, int koff, int voff, const bf16x8 (&qf)[DQK / 16], f32x16 (&o)[DV / 32], float& l0, float& l1, float& l2, float& l3) {
;     ...
;     vtr_wait<ND>(blo, bhi); VTR_SET(alo, ahi, vb, 0); PV_MMA(blo, bhi, pfa[3]); SM_CHUNK(sb, pfb[3], 3);
;     vtr_wait<ND>(alo, ahi); VTR_SET(blo, bhi, vb, 1); PV_MMA(alo, ahi, pfb[0]);
;     vtr_wait<ND>(blo, bhi); VTR_SET(alo, ahi, vb, 2); PV_MMA(blo, bhi, pfb[1]);
;     vtr_wait<ND>(alo, ahi); VTR_SET(blo, bhi, vb, 3); PV_MMA(alo, ahi, pfb[2]);
;     vtr_wait<ND>(blo, bhi); PV_MMA(blo, bhi, pfb[3]);
; template <int DQK, int DV, int kpitch, int vpitch>
; DI void attn_map(LAS unsigned char* lds, const bf16x8 (&qf)[DQK / 16], const bf16* Kg, const bf16* Vg, f32x16 (&o)[DV / 32], float& lsum, int tid, int lane) {
;     ...
;     for (int s = 0; s < NSTEP; ++s) {
;         asm volatile("s_waitcnt vmcnt(0)" ::: "memory");
;         __builtin_amdgcn_s_barrier();
;         asm volatile("" ::: "memory");
;         if (s + 1 < NSTEP) ATT_DMA2((s + 1) & 1);
;         const LAS unsigned char* ta = lds + (s & 1) * 2 * TILE;
;         attn_step2<DQK, DV, KSTR, VSTR>(ta, ta + TILE, koff, voff, qf, o, l0, l1, l2, l3);
;     }
	v_mfma_f32_32x32x16_bf16 v[16:31], v[194:197], v[168:171], v[16:31]
	ds_read_b64_tr_b16 v[194:195], v153 offset:32768
	ds_read_b64_tr_b16 v[196:197], v153 offset:34304
	v_add_f32_e32 v148, v148, v70
	v_exp_f32_e32 v80, v80
	v_exp_f32_e32 v81, v81
	v_exp_f32_e32 v82, v82
	s_waitcnt lgkmcnt(6)
	v_mfma_f32_32x32x16_bf16 v[0:15], v[198:201], v[168:171], v[0:15]
	ds_read_b64_tr_b16 v[198:199], v153 offset:32832
	ds_read_b64_tr_b16 v[200:201], v153 offset:34368
	v_exp_f32_e32 v83, v83
	v_exp_f32_e32 v84, v84
	v_exp_f32_e32 v85, v85
	s_waitcnt lgkmcnt(6)
	v_mfma_f32_32x32x16_bf16 v[16:31], v[156:159], v[172:175], v[16:31]
	ds_read_b64_tr_b16 v[156:157], v153 offset:35840
	ds_read_b64_tr_b16 v[158:159], v153 offset:37376
	v_exp_f32_e32 v86, v86
	v_exp_f32_e32 v87, v87
	v_exp_f32_e32 v88, v88
	s_waitcnt lgkmcnt(6)
	v_mfma_f32_32x32x16_bf16 v[0:15], v[160:163], v[172:175], v[0:15]
	ds_read_b64_tr_b16 v[160:161], v153 offset:35904
	ds_read_b64_tr_b16 v[162:163], v153 offset:37440
	v_exp_f32_e32 v89, v89
	v_exp_f32_e32 v90, v90
	v_exp_f32_e32 v91, v91
	s_waitcnt lgkmcnt(6)
	v_mfma_f32_32x32x16_bf16 v[16:31], v[194:197], v[128:131], v[16:31]
	ds_read_b64_tr_b16 v[194:195], v153 offset:38912
	ds_read_b64_tr_b16 v[196:197], v153 offset:40448
	v_exp_f32_e32 v92, v92
	v_exp_f32_e32 v93, v93
	v_exp_f32_e32 v94, v94
	s_waitcnt lgkmcnt(6)
	v_mfma_f32_32x32x16_bf16 v[0:15], v[198:201], v[128:131], v[0:15]
	ds_read_b64_tr_b16 v[198:199], v153 offset:38976
	ds_read_b64_tr_b16 v[200:201], v153 offset:40512
	v_exp_f32_e32 v95, v95
	v_cvt_pk_bf16_f32 v168, v80, v81
	v_cvt_pk_bf16_f32 v169, v82, v83
	v_cvt_pk_bf16_f32 v170, v84, v85
	v_cvt_pk_bf16_f32 v171, v86, v87
	s_waitcnt lgkmcnt(6)
	v_mfma_f32_32x32x16_bf16 v[16:31], v[156:159], v[132:135], v[16:31]
	ds_read_b64_tr_b16 v[156:157], v153 offset:41984
	ds_read_b64_tr_b16 v[158:159], v153 offset:43520
	v_cvt_pk_bf16_f32 v172, v88, v89
	v_cvt_pk_bf16_f32 v173, v90, v91
	v_cvt_pk_bf16_f32 v174, v92, v93
	v_cvt_pk_bf16_f32 v175, v94, v95
	v_add_f32_e32 v149, v149, v71
	v_add_f32_e32 v146, v146, v72
	s_waitcnt lgkmcnt(6)
	v_mfma_f32_32x32x16_bf16 v[0:15], v[160:163], v[132:135], v[0:15]
	ds_read_b64_tr_b16 v[160:161], v153 offset:42048
	ds_read_b64_tr_b16 v[162:163], v153 offset:43584
	v_add_f32_e32 v147, v147, v73
	v_add_f32_e32 v148, v148, v74
	v_add_f32_e32 v149, v149, v75
	v_add_f32_e32 v146, v146, v76
	v_add_f32_e32 v147, v147, v77
	v_add_f32_e32 v148, v148, v78
	s_waitcnt lgkmcnt(6)
	v_mfma_f32_32x32x16_bf16 v[16:31], v[194:197], v[168:171], v[16:31]
	v_add_f32_e32 v149, v149, v79
	v_add_f32_e32 v146, v146, v80
	v_add_f32_e32 v147, v147, v81
	v_add_f32_e32 v148, v148, v82
	v_add_f32_e32 v149, v149, v83
	v_add_f32_e32 v146, v146, v84
	s_waitcnt lgkmcnt(4)
	v_mfma_f32_32x32x16_bf16 v[0:15], v[198:201], v[168:171], v[0:15]
	v_add_f32_e32 v147, v147, v85
	v_add_f32_e32 v148, v148, v86
	v_add_f32_e32 v149, v149, v87
	v_add_f32_e32 v146, v146, v88
	v_add_f32_e32 v147, v147, v89
	v_add_f32_e32 v148, v148, v90
	s_waitcnt lgkmcnt(2)
	v_mfma_f32_32x32x16_bf16 v[16:31], v[156:159], v[172:175], v[16:31]
	v_add_f32_e32 v149, v149, v91
	v_add_f32_e32 v146, v146, v92
	v_add_f32_e32 v147, v147, v93
	v_add_f32_e32 v148, v148, v94
	v_add_f32_e32 v149, v149, v95
	s_waitcnt lgkmcnt(0)
	v_mfma_f32_32x32x16_bf16 v[0:15], v[160:163], v[172:175], v[0:15]
	s_cmp_lg_u32 s26, 0x100000
	s_mov_b32 s27, s26
	s_cbranch_scc0 .LBB0_1913
.LBB0_1953:
	s_waitcnt vmcnt(0)
	s_barrier
	s_add_i32 s26, s27, 0x10000
	s_branch .LBB0_1952
